# GEMM tile headers: accumulator zeroing with v_mov_b64 (64 instead of 128 moves); dropped two redundant pre-loop vmcnt(0) drains
# baseline (speedup 1.0000x reference)
; #define PG8_STAGE(bufoff, gbase) do { _Pragma("unroll") for (int _i = 0; _i < 2; ++_i) \
;         __builtin_amdgcn_global_load_lds((const unsigned*)((const char*)(gbase) + voff[_i]), (LAS unsigned*)(lds + (bufoff) + ldsw + _i * 8192), 16, 0, 0); } while (0)
; #define PG8_WAIT_V(n) asm volatile("s_waitcnt vmcnt(" #n ")" ::: "memory")
; #define PG8_BAR __builtin_amdgcn_s_barrier()
;     ...
;     f32x4 acc[2][2][4][2];
; #pragma unroll
;     for (int a = 0; a < 2; ++a)
; #pragma unroll
;         for (int b = 0; b < 2; ++b)
; #pragma unroll
;             for (int m = 0; m < 4; ++m)
; #pragma unroll
;                 for (int n = 0; n < 2; ++n) acc[a][b][m][n] = (f32x4){0.f, 0.f, 0.f, 0.f};
;     bf16x8 At[4][2], B0[2][2], B1[2][2];
;     const char* cA = (const char*)gA + (size_t)cur.pm * tstep; const char* cB = (const char*)gBt + (size_t)cur.pn * tstep;
;     PG8_STAGE(PG8_SB(0, 0), cB); PG8_STAGE(PG8_SA(0, 0), cA); PG8_STAGE(PG8_SB(0, 1), cB + hstep); PG8_STAGE(PG8_SA(0, 1), cA + hstep);
;     if (wr == 1) PG8_BAR;
;     PG8_WAIT_V(4); PG8_BAR;
;     PG8_STAGE(PG8_SB(1, 0), cB + kstep); PG8_STAGE(PG8_SA(1, 0), cA + kstep); PG8_STAGE(PG8_SB(1, 1), cB + hstep + kstep);
;     PG8_WAIT_V(6); PG8_BAR;
;     for (;;) {
;         const bool has_next = S.next(ui + 1, nxt);
;         const char* nA = has_next ? (const char*)gA + (size_t)nxt.pm * tstep : cA; const char* nB = has_next ? (const char*)gBt + (size_t)nxt.pn * tstep : cB;
.LBB0_160:
	s_ashr_i32 s53, s52, 31
	v_cmp_lt_i64_e32 vcc, s[14:15], v[136:137]
	s_lshl_b64 s[14:15], s[52:53], 19
	s_add_u32 s54, s24, s14
	s_addc_u32 s55, s25, s15
	s_and_b64 s[14:15], vcc, exec
	s_cselect_b32 s4, s55, s11
	s_cselect_b32 s7, s54, s10
	s_ashr_i32 s51, s50, 31
	s_lshl_b64 s[14:15], s[50:51], 19
	v_readlane_b32 s0, v251, 54
	v_readlane_b32 s1, v251, 55
	s_waitcnt lgkmcnt(0)
	s_add_u32 s56, s0, s14
	s_addc_u32 s57, s1, s15
	s_and_b64 s[14:15], vcc, exec
	s_cselect_b32 s18, s57, s13
	s_cselect_b32 s19, s56, s12
	s_add_u32 s10, s10, 0x40080
	s_addc_u32 s11, s11, 0
	s_add_u32 s22, s12, 0x100
	v_mov_b32_e32 v2, 0
	v_mov_b32_e32 v3, 0
	s_addc_u32 s23, s13, 0
	s_mov_b32 s28, -2
	v_mov_b64_e32 v[4:5], v[2:3]
	v_mov_b64_e32 v[6:7], v[2:3]
	v_mov_b64_e32 v[8:9], v[2:3]
	v_mov_b64_e32 v[10:11], v[2:3]
	v_mov_b64_e32 v[12:13], v[2:3]
	v_mov_b64_e32 v[14:15], v[2:3]
	v_mov_b64_e32 v[16:17], v[2:3]
	v_mov_b64_e32 v[18:19], v[2:3]
	v_mov_b64_e32 v[20:21], v[2:3]
	v_mov_b64_e32 v[22:23], v[2:3]
	v_mov_b64_e32 v[24:25], v[2:3]
	v_mov_b64_e32 v[26:27], v[2:3]
	v_mov_b64_e32 v[28:29], v[2:3]
	v_mov_b64_e32 v[30:31], v[2:3]
	v_mov_b64_e32 v[32:33], v[2:3]
	v_mov_b64_e32 v[34:35], v[2:3]
	v_mov_b64_e32 v[36:37], v[2:3]
	v_mov_b64_e32 v[38:39], v[2:3]
	v_mov_b64_e32 v[40:41], v[2:3]
	v_mov_b64_e32 v[42:43], v[2:3]
	v_mov_b64_e32 v[44:45], v[2:3]
	v_mov_b64_e32 v[46:47], v[2:3]
	v_mov_b64_e32 v[48:49], v[2:3]
	v_mov_b64_e32 v[50:51], v[2:3]
	v_mov_b64_e32 v[52:53], v[2:3]
	v_mov_b64_e32 v[54:55], v[2:3]
	v_mov_b64_e32 v[56:57], v[2:3]
	v_mov_b64_e32 v[58:59], v[2:3]
	v_mov_b64_e32 v[60:61], v[2:3]
	v_mov_b64_e32 v[62:63], v[2:3]
	v_mov_b64_e32 v[64:65], v[2:3]
	v_mov_b64_e32 v[66:67], v[2:3]
	v_mov_b64_e32 v[68:69], v[2:3]
	v_mov_b64_e32 v[70:71], v[2:3]
	v_mov_b64_e32 v[72:73], v[2:3]
	v_mov_b64_e32 v[74:75], v[2:3]
	v_mov_b64_e32 v[76:77], v[2:3]
	v_mov_b64_e32 v[78:79], v[2:3]
	v_mov_b64_e32 v[80:81], v[2:3]
	v_mov_b64_e32 v[82:83], v[2:3]
	v_mov_b64_e32 v[84:85], v[2:3]
	v_mov_b64_e32 v[86:87], v[2:3]
	v_mov_b64_e32 v[88:89], v[2:3]
	v_mov_b64_e32 v[90:91], v[2:3]
	v_mov_b64_e32 v[92:93], v[2:3]
	v_mov_b64_e32 v[94:95], v[2:3]
	v_mov_b64_e32 v[96:97], v[2:3]
	v_mov_b64_e32 v[98:99], v[2:3]
	v_mov_b64_e32 v[100:101], v[2:3]
	v_mov_b64_e32 v[102:103], v[2:3]
	v_mov_b64_e32 v[104:105], v[2:3]
	v_mov_b64_e32 v[106:107], v[2:3]
	v_mov_b64_e32 v[108:109], v[2:3]
	v_mov_b64_e32 v[110:111], v[2:3]
	v_mov_b64_e32 v[112:113], v[2:3]
	v_mov_b64_e32 v[114:115], v[2:3]
	v_mov_b64_e32 v[116:117], v[2:3]
	v_mov_b64_e32 v[118:119], v[2:3]
	v_mov_b64_e32 v[120:121], v[2:3]
	v_mov_b64_e32 v[122:123], v[2:3]
	v_mov_b64_e32 v[124:125], v[2:3]
	v_mov_b64_e32 v[126:127], v[2:3]
	v_mov_b64_e32 v[128:129], v[2:3]

; #define PG8_STAGE(bufoff, gbase) do { _Pragma("unroll") for (int _i = 0; _i < 2; ++_i) \
;         __builtin_amdgcn_global_load_lds((const unsigned*)((const char*)(gbase) + voff[_i]), (LAS unsigned*)(lds + (bufoff) + ldsw + _i * 8192), 16, 0, 0); } while (0)
; #define PG8_WAIT_V(n) asm volatile("s_waitcnt vmcnt(" #n ")" ::: "memory")
; #define PG8_BAR __builtin_amdgcn_s_barrier()
;     ...
;     f32x4 acc[2][2][4][2];
; #pragma unroll
;     for (int a = 0; a < 2; ++a)
; #pragma unroll
;         for (int b = 0; b < 2; ++b)
; #pragma unroll
;             for (int m = 0; m < 4; ++m)
; #pragma unroll
;                 for (int n = 0; n < 2; ++n) acc[a][b][m][n] = (f32x4){0.f, 0.f, 0.f, 0.f};
;     bf16x8 At[4][2], B0[2][2], B1[2][2];
;     const char* cA = (const char*)gA + (size_t)cur.pm * tstep; const char* cB = (const char*)gBt + (size_t)cur.pn * tstep;
;     PG8_STAGE(PG8_SB(0, 0), cB); PG8_STAGE(PG8_SA(0, 0), cA); PG8_STAGE(PG8_SB(0, 1), cB + hstep); PG8_STAGE(PG8_SA(0, 1), cA + hstep);
;     if (wr == 1) PG8_BAR;
;     PG8_WAIT_V(4); PG8_BAR;
;     PG8_STAGE(PG8_SB(1, 0), cB + kstep); PG8_STAGE(PG8_SA(1, 0), cA + kstep); PG8_STAGE(PG8_SB(1, 1), cB + hstep + kstep);
;     PG8_WAIT_V(6); PG8_BAR;
;     for (;;) {
;         const bool has_next = S.next(ui + 1, nxt);
;         const char* nA = has_next ? (const char*)gA + (size_t)nxt.pm * tstep : cA; const char* nB = has_next ? (const char*)gBt + (size_t)nxt.pn * tstep : cB;
.LBB0_481:
	s_ashr_i32 s59, s58, 31
	v_cmp_lt_i64_e32 vcc, s[14:15], v[140:141]
	s_lshl_b64 s[14:15], s[58:59], 19
	s_add_u32 s60, s24, s14
	s_addc_u32 s61, s25, s15
	s_and_b64 s[14:15], vcc, exec
	s_cselect_b32 s4, s61, s11
	s_cselect_b32 s7, s60, s10
	s_waitcnt lgkmcnt(0)
	s_ashr_i32 s57, s56, 31
	s_lshl_b64 s[14:15], s[56:57], 19
	s_add_u32 s62, s17, s14
	s_addc_u32 s63, s20, s15
	s_and_b64 s[14:15], vcc, exec
	s_cselect_b32 s18, s63, s13
	s_cselect_b32 s19, s62, s12
	s_add_u32 s10, s10, 0x40080
	s_addc_u32 s11, s11, 0
	s_add_u32 s22, s12, 0x100
	v_mov_b32_e32 v2, 0
	v_mov_b32_e32 v3, 0
	s_addc_u32 s23, s13, 0
	s_mov_b32 s28, -2
	v_mov_b64_e32 v[4:5], v[2:3]
	v_mov_b64_e32 v[6:7], v[2:3]
	v_mov_b64_e32 v[8:9], v[2:3]
	v_mov_b64_e32 v[10:11], v[2:3]
	v_mov_b64_e32 v[12:13], v[2:3]
	v_mov_b64_e32 v[14:15], v[2:3]
	v_mov_b64_e32 v[16:17], v[2:3]
	v_mov_b64_e32 v[18:19], v[2:3]
	v_mov_b64_e32 v[20:21], v[2:3]
	v_mov_b64_e32 v[22:23], v[2:3]
	v_mov_b64_e32 v[24:25], v[2:3]
	v_mov_b64_e32 v[26:27], v[2:3]
	v_mov_b64_e32 v[28:29], v[2:3]
	v_mov_b64_e32 v[30:31], v[2:3]
	v_mov_b64_e32 v[32:33], v[2:3]
	v_mov_b64_e32 v[34:35], v[2:3]
	v_mov_b64_e32 v[36:37], v[2:3]
	v_mov_b64_e32 v[38:39], v[2:3]
	v_mov_b64_e32 v[40:41], v[2:3]
	v_mov_b64_e32 v[42:43], v[2:3]
	v_mov_b64_e32 v[44:45], v[2:3]
	v_mov_b64_e32 v[46:47], v[2:3]
	v_mov_b64_e32 v[48:49], v[2:3]
	v_mov_b64_e32 v[50:51], v[2:3]
	v_mov_b64_e32 v[52:53], v[2:3]
	v_mov_b64_e32 v[54:55], v[2:3]
	v_mov_b64_e32 v[56:57], v[2:3]
	v_mov_b64_e32 v[58:59], v[2:3]
	v_mov_b64_e32 v[60:61], v[2:3]
	v_mov_b64_e32 v[62:63], v[2:3]
	v_mov_b64_e32 v[64:65], v[2:3]
	v_mov_b64_e32 v[66:67], v[2:3]
	v_mov_b64_e32 v[68:69], v[2:3]
	v_mov_b64_e32 v[70:71], v[2:3]
	v_mov_b64_e32 v[72:73], v[2:3]
	v_mov_b64_e32 v[74:75], v[2:3]
	v_mov_b64_e32 v[76:77], v[2:3]
	v_mov_b64_e32 v[78:79], v[2:3]
	v_mov_b64_e32 v[80:81], v[2:3]
	v_mov_b64_e32 v[82:83], v[2:3]
	v_mov_b64_e32 v[84:85], v[2:3]
	v_mov_b64_e32 v[86:87], v[2:3]
	v_mov_b64_e32 v[88:89], v[2:3]
	v_mov_b64_e32 v[90:91], v[2:3]
	v_mov_b64_e32 v[92:93], v[2:3]
	v_mov_b64_e32 v[94:95], v[2:3]
	v_mov_b64_e32 v[96:97], v[2:3]
	v_mov_b64_e32 v[98:99], v[2:3]
	v_mov_b64_e32 v[100:101], v[2:3]
	v_mov_b64_e32 v[102:103], v[2:3]
	v_mov_b64_e32 v[104:105], v[2:3]
	v_mov_b64_e32 v[106:107], v[2:3]
	v_mov_b64_e32 v[108:109], v[2:3]
	v_mov_b64_e32 v[110:111], v[2:3]
	v_mov_b64_e32 v[112:113], v[2:3]
	v_mov_b64_e32 v[114:115], v[2:3]
	v_mov_b64_e32 v[116:117], v[2:3]
	v_mov_b64_e32 v[118:119], v[2:3]
	v_mov_b64_e32 v[120:121], v[2:3]
	v_mov_b64_e32 v[122:123], v[2:3]
	v_mov_b64_e32 v[124:125], v[2:3]
	v_mov_b64_e32 v[126:127], v[2:3]
	v_mov_b64_e32 v[128:129], v[2:3]

; #define PG8_STAGE(bufoff, gbase) do { _Pragma("unroll") for (int _i = 0; _i < 2; ++_i) \
;         __builtin_amdgcn_global_load_lds((const unsigned*)((const char*)(gbase) + voff[_i]), (LAS unsigned*)(lds + (bufoff) + ldsw + _i * 8192), 16, 0, 0); } while (0)
; #define PG8_WAIT_V(n) asm volatile("s_waitcnt vmcnt(" #n ")" ::: "memory")
; #define PG8_BAR __builtin_amdgcn_s_barrier()
;     ...
;     f32x4 acc[2][2][4][2];
; #pragma unroll
;     for (int a = 0; a < 2; ++a)
; #pragma unroll
;         for (int b = 0; b < 2; ++b)
; #pragma unroll
;             for (int m = 0; m < 4; ++m)
; #pragma unroll
;                 for (int n = 0; n < 2; ++n) acc[a][b][m][n] = (f32x4){0.f, 0.f, 0.f, 0.f};
;     bf16x8 At[4][2], B0[2][2], B1[2][2];
;     const char* cA = (const char*)gA + (size_t)cur.pm * tstep; const char* cB = (const char*)gBt + (size_t)cur.pn * tstep;
;     PG8_STAGE(PG8_SB(0, 0), cB); PG8_STAGE(PG8_SA(0, 0), cA); PG8_STAGE(PG8_SB(0, 1), cB + hstep); PG8_STAGE(PG8_SA(0, 1), cA + hstep);
;     if (wr == 1) PG8_BAR;
;     PG8_WAIT_V(4); PG8_BAR;
;     PG8_STAGE(PG8_SB(1, 0), cB + kstep); PG8_STAGE(PG8_SA(1, 0), cA + kstep); PG8_STAGE(PG8_SB(1, 1), cB + hstep + kstep);
;     PG8_WAIT_V(6); PG8_BAR;
;     for (;;) {
;         const bool has_next = S.next(ui + 1, nxt);
;         const char* nA = has_next ? (const char*)gA + (size_t)nxt.pm * tstep : cA; const char* nB = has_next ? (const char*)gBt + (size_t)nxt.pn * tstep : cB;
.LBB0_758:
	s_ashr_i32 s65, s64, 31
	v_cmp_lt_i64_e32 vcc, s[14:15], v[140:141]
	s_lshl_b64 s[14:15], s[64:65], 19
	s_add_u32 s66, s24, s14
	s_addc_u32 s67, s25, s15
	s_and_b64 s[14:15], vcc, exec
	s_cselect_b32 s18, s67, s11
	s_cselect_b32 s19, s66, s10
	s_ashr_i32 s63, s62, 31
	s_lshl_b64 s[14:15], s[62:63], 19
	s_add_u32 s68, s60, s14
	s_addc_u32 s69, s61, s15
	s_and_b64 s[14:15], vcc, exec
	s_cselect_b32 s22, s69, s13
	s_cselect_b32 s23, s68, s12
	s_add_u32 s10, s10, 0x40080
	s_addc_u32 s11, s11, 0
	s_add_u32 s28, s12, 0x100
	v_mov_b32_e32 v2, 0
	v_mov_b32_e32 v3, 0
	s_addc_u32 s29, s13, 0
	s_mov_b32 s30, -2
	v_mov_b64_e32 v[4:5], v[2:3]
	v_mov_b64_e32 v[6:7], v[2:3]
	v_mov_b64_e32 v[8:9], v[2:3]
	v_mov_b64_e32 v[10:11], v[2:3]
	v_mov_b64_e32 v[12:13], v[2:3]
	v_mov_b64_e32 v[14:15], v[2:3]
	v_mov_b64_e32 v[16:17], v[2:3]
	v_mov_b64_e32 v[18:19], v[2:3]
	v_mov_b64_e32 v[20:21], v[2:3]
	v_mov_b64_e32 v[22:23], v[2:3]
	v_mov_b64_e32 v[24:25], v[2:3]
	v_mov_b64_e32 v[26:27], v[2:3]
	v_mov_b64_e32 v[28:29], v[2:3]
	v_mov_b64_e32 v[30:31], v[2:3]
	v_mov_b64_e32 v[32:33], v[2:3]
	v_mov_b64_e32 v[34:35], v[2:3]
	v_mov_b64_e32 v[36:37], v[2:3]
	v_mov_b64_e32 v[38:39], v[2:3]
	v_mov_b64_e32 v[40:41], v[2:3]
	v_mov_b64_e32 v[42:43], v[2:3]
	v_mov_b64_e32 v[44:45], v[2:3]
	v_mov_b64_e32 v[46:47], v[2:3]
	v_mov_b64_e32 v[48:49], v[2:3]
	v_mov_b64_e32 v[50:51], v[2:3]
	v_mov_b64_e32 v[52:53], v[2:3]
	v_mov_b64_e32 v[54:55], v[2:3]
	v_mov_b64_e32 v[56:57], v[2:3]
	v_mov_b64_e32 v[58:59], v[2:3]
	v_mov_b64_e32 v[60:61], v[2:3]
	v_mov_b64_e32 v[62:63], v[2:3]
	v_mov_b64_e32 v[64:65], v[2:3]
	v_mov_b64_e32 v[66:67], v[2:3]
	v_mov_b64_e32 v[68:69], v[2:3]
	v_mov_b64_e32 v[70:71], v[2:3]
	v_mov_b64_e32 v[72:73], v[2:3]
	v_mov_b64_e32 v[74:75], v[2:3]
	v_mov_b64_e32 v[76:77], v[2:3]
	v_mov_b64_e32 v[78:79], v[2:3]
	v_mov_b64_e32 v[80:81], v[2:3]
	v_mov_b64_e32 v[82:83], v[2:3]
	v_mov_b64_e32 v[84:85], v[2:3]
	v_mov_b64_e32 v[86:87], v[2:3]
	v_mov_b64_e32 v[88:89], v[2:3]
	v_mov_b64_e32 v[90:91], v[2:3]
	v_mov_b64_e32 v[92:93], v[2:3]
	v_mov_b64_e32 v[94:95], v[2:3]
	v_mov_b64_e32 v[96:97], v[2:3]
	v_mov_b64_e32 v[98:99], v[2:3]
	v_mov_b64_e32 v[100:101], v[2:3]
	v_mov_b64_e32 v[102:103], v[2:3]
	v_mov_b64_e32 v[104:105], v[2:3]
	v_mov_b64_e32 v[106:107], v[2:3]
	v_mov_b64_e32 v[108:109], v[2:3]
	v_mov_b64_e32 v[110:111], v[2:3]
	v_mov_b64_e32 v[112:113], v[2:3]
	v_mov_b64_e32 v[114:115], v[2:3]
	v_mov_b64_e32 v[116:117], v[2:3]
	v_mov_b64_e32 v[118:119], v[2:3]
	v_mov_b64_e32 v[120:121], v[2:3]
	v_mov_b64_e32 v[122:123], v[2:3]
	v_mov_b64_e32 v[124:125], v[2:3]
	v_mov_b64_e32 v[126:127], v[2:3]
	v_mov_b64_e32 v[128:129], v[2:3]

; #define PG8_STAGE(bufoff, gbase) do { _Pragma("unroll") for (int _i = 0; _i < 2; ++_i) \
;         __builtin_amdgcn_global_load_lds((const unsigned*)((const char*)(gbase) + voff[_i]), (LAS unsigned*)(lds + (bufoff) + ldsw + _i * 8192), 16, 0, 0); } while (0)
; #define PG8_WAIT_V(n) asm volatile("s_waitcnt vmcnt(" #n ")" ::: "memory")
; #define PG8_BAR __builtin_amdgcn_s_barrier()
;     ...
;     f32x4 acc[2][2][4][2];
; #pragma unroll
;     for (int a = 0; a < 2; ++a)
; #pragma unroll
;         for (int b = 0; b < 2; ++b)
; #pragma unroll
;             for (int m = 0; m < 4; ++m)
; #pragma unroll
;                 for (int n = 0; n < 2; ++n) acc[a][b][m][n] = (f32x4){0.f, 0.f, 0.f, 0.f};
;     bf16x8 At[4][2], B0[2][2], B1[2][2];
;     const char* cA = (const char*)gA + (size_t)cur.pm * tstep; const char* cB = (const char*)gBt + (size_t)cur.pn * tstep;
;     PG8_STAGE(PG8_SB(0, 0), cB); PG8_STAGE(PG8_SA(0, 0), cA); PG8_STAGE(PG8_SB(0, 1), cB + hstep); PG8_STAGE(PG8_SA(0, 1), cA + hstep);
;     if (wr == 1) PG8_BAR;
;     PG8_WAIT_V(4); PG8_BAR;
;     PG8_STAGE(PG8_SB(1, 0), cB + kstep); PG8_STAGE(PG8_SA(1, 0), cA + kstep); PG8_STAGE(PG8_SB(1, 1), cB + hstep + kstep);
;     PG8_WAIT_V(6); PG8_BAR;
;     for (;;) {
;         const bool has_next = S.next(ui + 1, nxt);
;         const char* nA = has_next ? (const char*)gA + (size_t)nxt.pm * tstep : cA; const char* nB = has_next ? (const char*)gBt + (size_t)nxt.pn * tstep : cB;
.LBB0_903:
	s_ashr_i32 s15, s14, 31
	v_cmp_lt_i64_e32 vcc, s[40:41], v[144:145]
	s_lshl_b64 s[40:41], s[14:15], 19
	s_add_u32 s40, s24, s40
	s_addc_u32 s41, s25, s41
	s_and_b64 s[46:47], vcc, exec
	s_cselect_b32 s15, s41, s55
	s_cselect_b32 s31, s40, s54
	s_ashr_i32 s13, s12, 31
	s_lshl_b64 s[46:47], s[12:13], 19
	s_add_u32 s46, s5, s46
	s_addc_u32 s47, s7, s47
	s_and_b64 s[58:59], vcc, exec
	s_cselect_b32 s13, s47, s57
	s_cselect_b32 s36, s46, s56
	s_add_u32 s54, s54, 0x40080
	s_addc_u32 s55, s55, 0
	s_add_u32 s60, s56, 0x100
	v_mov_b32_e32 v2, 0
	v_mov_b32_e32 v3, 0
	s_addc_u32 s61, s57, 0
	s_mov_b32 s62, -2
	v_mov_b64_e32 v[4:5], v[2:3]
	v_mov_b64_e32 v[6:7], v[2:3]
	v_mov_b64_e32 v[8:9], v[2:3]
	v_mov_b64_e32 v[10:11], v[2:3]
	v_mov_b64_e32 v[12:13], v[2:3]
	v_mov_b64_e32 v[14:15], v[2:3]
	v_mov_b64_e32 v[16:17], v[2:3]
	v_mov_b64_e32 v[18:19], v[2:3]
	v_mov_b64_e32 v[20:21], v[2:3]
	v_mov_b64_e32 v[22:23], v[2:3]
	v_mov_b64_e32 v[24:25], v[2:3]
	v_mov_b64_e32 v[26:27], v[2:3]
	v_mov_b64_e32 v[28:29], v[2:3]
	v_mov_b64_e32 v[30:31], v[2:3]
	v_mov_b64_e32 v[32:33], v[2:3]
	v_mov_b64_e32 v[34:35], v[2:3]
	v_mov_b64_e32 v[36:37], v[2:3]
	v_mov_b64_e32 v[38:39], v[2:3]
	v_mov_b64_e32 v[40:41], v[2:3]
	v_mov_b64_e32 v[42:43], v[2:3]
	v_mov_b64_e32 v[44:45], v[2:3]
	v_mov_b64_e32 v[46:47], v[2:3]
	v_mov_b64_e32 v[48:49], v[2:3]
	v_mov_b64_e32 v[50:51], v[2:3]
	v_mov_b64_e32 v[52:53], v[2:3]
	v_mov_b64_e32 v[54:55], v[2:3]
	v_mov_b64_e32 v[56:57], v[2:3]
	v_mov_b64_e32 v[58:59], v[2:3]
	v_mov_b64_e32 v[60:61], v[2:3]
	v_mov_b64_e32 v[62:63], v[2:3]
	v_mov_b64_e32 v[64:65], v[2:3]
	v_mov_b64_e32 v[66:67], v[2:3]
	v_mov_b64_e32 v[68:69], v[2:3]
	v_mov_b64_e32 v[70:71], v[2:3]
	v_mov_b64_e32 v[72:73], v[2:3]
	v_mov_b64_e32 v[74:75], v[2:3]
	v_mov_b64_e32 v[76:77], v[2:3]
	v_mov_b64_e32 v[78:79], v[2:3]
	v_mov_b64_e32 v[80:81], v[2:3]
	v_mov_b64_e32 v[82:83], v[2:3]
	v_mov_b64_e32 v[84:85], v[2:3]
	v_mov_b64_e32 v[86:87], v[2:3]
	v_mov_b64_e32 v[88:89], v[2:3]
	v_mov_b64_e32 v[90:91], v[2:3]
	v_mov_b64_e32 v[92:93], v[2:3]
	v_mov_b64_e32 v[94:95], v[2:3]
	v_mov_b64_e32 v[96:97], v[2:3]
	v_mov_b64_e32 v[98:99], v[2:3]
	v_mov_b64_e32 v[100:101], v[2:3]
	v_mov_b64_e32 v[102:103], v[2:3]
	v_mov_b64_e32 v[104:105], v[2:3]
	v_mov_b64_e32 v[106:107], v[2:3]
	v_mov_b64_e32 v[108:109], v[2:3]
	v_mov_b64_e32 v[110:111], v[2:3]
	v_mov_b64_e32 v[112:113], v[2:3]
	v_mov_b64_e32 v[114:115], v[2:3]
	v_mov_b64_e32 v[116:117], v[2:3]
	v_mov_b64_e32 v[118:119], v[2:3]
	v_mov_b64_e32 v[120:121], v[2:3]
	v_mov_b64_e32 v[122:123], v[2:3]
	v_mov_b64_e32 v[124:125], v[2:3]
	v_mov_b64_e32 v[126:127], v[2:3]
	v_mov_b64_e32 v[128:129], v[2:3]

; #define PG8_STAGE(bufoff, gbase) do { _Pragma("unroll") for (int _i = 0; _i < 2; ++_i) \
;         __builtin_amdgcn_global_load_lds((const unsigned*)((const char*)(gbase) + voff[_i]), (LAS unsigned*)(lds + (bufoff) + ldsw + _i * 8192), 16, 0, 0); } while (0)
; #define PG8_WAIT_V(n) asm volatile("s_waitcnt vmcnt(" #n ")" ::: "memory")
; #define PG8_BAR __builtin_amdgcn_s_barrier()
;     __device__ bool next(int i, Unit& u) const {
;         const long L = (long)i * G + c; if (L >= nwg) return false;
;         int wgid = (int)L; { const int q = nwg / 8, r = nwg % 8, xcd = wgid % 8, off = wgid / 8; wgid = (xcd < r ? xcd * (q + 1) : r * (q + 1) + (xcd - r) * q) + off; }
;         const int nig = 8 * nN, gid = wgid / nig, fm = gid * 8, gsz = (nM - fm) < 8 ? (nM - fm) : 8;
;         u.pm = fm + ((wgid % nig) % gsz); u.pn = (wgid % nig) / gsz; return true;
;     }
;     ...
;     const char* cA = (const char*)gA + (size_t)cur.pm * tstep; const char* cB = (const char*)gBt + (size_t)cur.pn * tstep;
;     PG8_STAGE(PG8_SB(0, 0), cB); PG8_STAGE(PG8_SA(0, 0), cA); PG8_STAGE(PG8_SB(0, 1), cB + hstep); PG8_STAGE(PG8_SA(0, 1), cA + hstep);
;     if (wr == 1) PG8_BAR;
;     PG8_WAIT_V(4); PG8_BAR;
;     PG8_STAGE(PG8_SB(1, 0), cB + kstep); PG8_STAGE(PG8_SA(1, 0), cA + kstep); PG8_STAGE(PG8_SB(1, 1), cB + hstep + kstep);
;     PG8_WAIT_V(6); PG8_BAR;
;     for (;;) {
;         const bool has_next = S.next(ui + 1, nxt);
;         const char* nA = has_next ? (const char*)gA + (size_t)nxt.pm * tstep : cA; const char* nB = has_next ? (const char*)gBt + (size_t)nxt.pn * tstep : cB;
.LBB0_1047:
	v_bfe_u32 v18, v8, 4, 2
	v_and_b32_e32 v9, 15, v8
	v_lshlrev_b32_e32 v19, 4, v18
	v_lshlrev_b32_e32 v8, 2, v8
	v_lshl_or_b32 v1, s7, 6, v9
	v_lshl_or_b32 v9, v9, 6, v19
	s_lshl_b32 s0, s7, 13
	v_and_b32_e32 v8, 32, v8
	v_bitop3_b32 v19, v9, s0, v8 bitop3:0xde
	s_lshl_b32 s0, s4, 5
	v_mov_b32_e32 v133, v0
	s_and_b32 s0, s0, 0x60
	v_lshl_add_u64 v[10:11], s[12:13], 0, v[132:133]
	v_mov_b32_e32 v131, v0
	s_lshl_b32 s1, s0, 7
	v_lshl_add_u64 v[12:13], s[12:13], 0, v[130:131]
	v_bitop3_b32 v158, v9, s1, v8 bitop3:0xde
	s_add_i32 m0, s17, 0x18000
	v_lshl_add_u64 v[8:9], v[10:11], 0, s[88:89]
	v_lshl_add_u64 v[14:15], s[10:11], 0, v[132:133]
	s_waitcnt vmcnt(4)
	s_barrier
	global_load_lds_dwordx4 v[8:9], off
	v_lshl_add_u64 v[8:9], v[12:13], 0, s[88:89]
	s_add_i32 m0, s17, 0x1a000
	s_add_i32 s67, s17, 0x8000
	s_add_i32 s68, s17, 0xa000
	v_lshl_add_u64 v[16:17], s[10:11], 0, v[130:131]
	global_load_lds_dwordx4 v[8:9], off
	v_lshl_add_u64 v[8:9], v[14:15], 0, s[88:89]
	s_mov_b32 m0, s67
	s_add_u32 s14, s12, 0x40080
	global_load_lds_dwordx4 v[8:9], off
	v_lshl_add_u64 v[8:9], v[16:17], 0, s[88:89]
	s_mov_b32 m0, s68
	s_addc_u32 s15, s13, 0
	global_load_lds_dwordx4 v[8:9], off
	s_add_i32 m0, s17, 0x1c000
	v_lshl_add_u64 v[8:9], s[14:15], 0, v[132:133]
	global_load_lds_dwordx4 v[8:9], off
	v_lshl_add_u64 v[8:9], s[14:15], 0, v[130:131]
	s_add_i32 m0, s17, 0x1e000
	v_lshl_or_b32 v159, v18, 2, s0
	global_load_lds_dwordx4 v[8:9], off
	v_lshlrev_b32_e32 v8, 14, v5
	v_and_b32_e32 v8, 0xffff8000, v8
	v_lshl_add_u32 v6, v6, 11, v8
	v_and_b32_e32 v5, 1, v5
	v_lshl_or_b32 v5, v5, 6, v6
	v_lshl_add_u32 v150, v7, 1, v5
	v_lshlrev_b32_e32 v5, 14, v2
	v_and_b32_e32 v5, 0xffff8000, v5
	s_waitcnt vmcnt(6)
	v_lshl_add_u32 v3, v3, 11, v5
	v_and_b32_e32 v2, 1, v2
	v_lshl_or_b32 v2, v2, 6, v3
	v_readlane_b32 s0, v252, 51
	v_mov_b32_e32 v151, v0
	v_lshl_add_u32 v152, v4, 1, v2
	v_mov_b32_e32 v153, v0
	s_mov_b32 s69, 0
	v_add_u32_e32 v160, 0, v19
	v_readlane_b32 s4, v252, 46
	s_mov_b32 s7, s0
	s_barrier
	v_readlane_b32 s1, v252, 52
.LBB0_1048:
	s_add_i32 s69, s69, 1
	v_readlane_b32 s0, v252, 50
	v_readlane_b32 s8, v252, 49
	s_mul_i32 s0, s69, s0
	s_mul_hi_u32 s1, s69, s8
	s_add_i32 s1, s1, s0
	s_mul_i32 s0, s69, s8
	v_readlane_b32 s8, v252, 45
	s_add_u32 s14, s0, s8
	v_readlane_b32 s0, v252, 44
	s_addc_u32 s15, s1, s0
	v_cmp_gt_i64_e64 s[44:45], s[14:15], v[146:147]
	s_and_b64 vcc, exec, s[44:45]
	s_cbranch_vccnz .LBB0_1050
	s_ashr_i32 s0, s14, 31
	s_lshr_b32 s0, s0, 29
	s_add_i32 s0, s14, s0
	s_ashr_i32 s1, s0, 3
	s_and_b32 s0, s0, -8
	s_sub_i32 s0, s14, s0
	s_cmp_lt_i32 s0, 0
	s_movk_i32 s8, 0x51
	s_cselect_b32 s18, s8, 0x50
	s_mul_i32 s0, s18, s0
	s_add_i32 s0, s0, s1
	s_mul_hi_i32 s1, s0, 0x66666667
	s_lshr_b32 s18, s1, 31
	s_ashr_i32 s1, s1, 4
	s_add_i32 s1, s1, s18
	s_lshl_b32 s18, s1, 3
	s_sub_i32 s19, 0x80, s18
	s_min_i32 s19, s19, 8
	s_abs_i32 s22, s19
	v_cvt_f32_u32_e32 v2, s22
	s_sub_i32 s28, 0, s22
	s_mul_i32 s1, s1, 40
	s_sub_i32 s0, s0, s1
	v_rcp_iflag_f32_e32 v2, v2
	s_abs_i32 s1, s0
	s_xor_b32 s23, s0, s19
	s_ashr_i32 s23, s23, 31
	v_mul_f32_e32 v2, 0x4f7ffffe, v2
	v_cvt_u32_f32_e32 v2, v2
	s_nop 0
	v_readfirstlane_b32 s29, v2
	s_mul_i32 s28, s28, s29
	s_mul_hi_u32 s28, s29, s28
	s_add_i32 s29, s29, s28
	s_mul_hi_u32 s28, s1, s29
	s_mul_i32 s29, s28, s22
	s_sub_i32 s1, s1, s29
	s_add_i32 s30, s28, 1
	s_sub_i32 s29, s1, s22
	s_cmp_ge_u32 s1, s22
	s_cselect_b32 s28, s30, s28
	s_cselect_b32 s1, s29, s1
	s_add_i32 s29, s28, 1
	s_cmp_ge_u32 s1, s22
	s_cselect_b32 s1, s29, s28
	s_xor_b32 s1, s1, s23
	s_sub_i32 s48, s1, s23
	s_mul_i32 s1, s48, s19
	s_sub_i32 s0, s0, s1
	s_add_i32 s60, s0, s18
.LBB0_1050:
	s_ashr_i32 s61, s60, 31
	v_cmp_lt_i64_e32 vcc, s[14:15], v[148:149]
	s_lshl_b64 s[14:15], s[60:61], 19
	s_add_u32 s62, s54, s14
	s_addc_u32 s63, s55, s15
	s_and_b64 s[14:15], vcc, exec
	s_cselect_b32 s18, s63, s11
	s_cselect_b32 s19, s62, s10
	s_ashr_i32 s49, s48, 31
	s_lshl_b64 s[14:15], s[48:49], 19
	s_add_u32 s64, s46, s14
	s_addc_u32 s65, s47, s15
	s_and_b64 s[14:15], vcc, exec
	s_cselect_b32 s22, s65, s13
	s_cselect_b32 s23, s64, s12
	s_add_u32 s10, s10, 0x40080
	s_addc_u32 s11, s11, 0
	s_add_u32 s28, s12, 0x100
	v_mov_b32_e32 v2, 0
	v_mov_b32_e32 v3, 0
	s_addc_u32 s29, s13, 0
	s_mov_b32 s30, -2
	v_mov_b64_e32 v[4:5], v[2:3]
	v_mov_b64_e32 v[6:7], v[2:3]
	v_mov_b64_e32 v[8:9], v[2:3]
	v_mov_b64_e32 v[10:11], v[2:3]
	v_mov_b64_e32 v[12:13], v[2:3]
	v_mov_b64_e32 v[14:15], v[2:3]
	v_mov_b64_e32 v[16:17], v[2:3]
	v_mov_b64_e32 v[18:19], v[2:3]
	v_mov_b64_e32 v[20:21], v[2:3]
	v_mov_b64_e32 v[22:23], v[2:3]
	v_mov_b64_e32 v[24:25], v[2:3]
	v_mov_b64_e32 v[26:27], v[2:3]
	v_mov_b64_e32 v[28:29], v[2:3]
	v_mov_b64_e32 v[30:31], v[2:3]
	v_mov_b64_e32 v[32:33], v[2:3]
	v_mov_b64_e32 v[34:35], v[2:3]
	v_mov_b64_e32 v[36:37], v[2:3]
	v_mov_b64_e32 v[38:39], v[2:3]
	v_mov_b64_e32 v[40:41], v[2:3]
	v_mov_b64_e32 v[42:43], v[2:3]
	v_mov_b64_e32 v[44:45], v[2:3]
	v_mov_b64_e32 v[46:47], v[2:3]
	v_mov_b64_e32 v[48:49], v[2:3]
	v_mov_b64_e32 v[50:51], v[2:3]
	v_mov_b64_e32 v[52:53], v[2:3]
	v_mov_b64_e32 v[54:55], v[2:3]
	v_mov_b64_e32 v[56:57], v[2:3]
	v_mov_b64_e32 v[58:59], v[2:3]
	v_mov_b64_e32 v[60:61], v[2:3]
	v_mov_b64_e32 v[62:63], v[2:3]
	v_mov_b64_e32 v[64:65], v[2:3]
	v_mov_b64_e32 v[66:67], v[2:3]
	v_mov_b64_e32 v[68:69], v[2:3]
	v_mov_b64_e32 v[70:71], v[2:3]
	v_mov_b64_e32 v[72:73], v[2:3]
	v_mov_b64_e32 v[74:75], v[2:3]
	v_mov_b64_e32 v[76:77], v[2:3]
	v_mov_b64_e32 v[78:79], v[2:3]
	v_mov_b64_e32 v[80:81], v[2:3]
	v_mov_b64_e32 v[82:83], v[2:3]
	v_mov_b64_e32 v[84:85], v[2:3]
	v_mov_b64_e32 v[86:87], v[2:3]
	v_mov_b64_e32 v[88:89], v[2:3]
	v_mov_b64_e32 v[90:91], v[2:3]
	v_mov_b64_e32 v[92:93], v[2:3]
	v_mov_b64_e32 v[94:95], v[2:3]
	v_mov_b64_e32 v[96:97], v[2:3]
	v_mov_b64_e32 v[98:99], v[2:3]
	v_mov_b64_e32 v[100:101], v[2:3]
	v_mov_b64_e32 v[102:103], v[2:3]
	v_mov_b64_e32 v[104:105], v[2:3]
	v_mov_b64_e32 v[106:107], v[2:3]
	v_mov_b64_e32 v[108:109], v[2:3]
	v_mov_b64_e32 v[110:111], v[2:3]
	v_mov_b64_e32 v[112:113], v[2:3]
	v_mov_b64_e32 v[114:115], v[2:3]
	v_mov_b64_e32 v[116:117], v[2:3]
	v_mov_b64_e32 v[118:119], v[2:3]
	v_mov_b64_e32 v[120:121], v[2:3]
	v_mov_b64_e32 v[122:123], v[2:3]
	v_mov_b64_e32 v[124:125], v[2:3]
	v_mov_b64_e32 v[126:127], v[2:3]
	v_mov_b64_e32 v[128:129], v[2:3]

;     ...
; #pragma unroll
;         for (int a = 0; a < 2; ++a)
; #pragma unroll
;             for (int b = 0; b < 2; ++b)
; #pragma unroll
;                 for (int m = 0; m < 4; ++m)
; #pragma unroll
;                     for (int n = 0; n < 2; ++n) acc[a][b][m][n] = (f32x4){0.f, 0.f, 0.f, 0.f};
;         cur = nxt; cA = nA; cB = nB; ++ui;
.LBB0_1244:
	s_add_u32 s40, s40, 0x80
	s_addc_u32 s41, s41, 0
	s_add_u32 s58, s58, 0x100
	v_mov_b32_e32 v2, 0
	v_mov_b32_e32 v3, 0
	s_addc_u32 s59, s59, 0
	s_mov_b32 s46, 0
	v_mov_b64_e32 v[4:5], v[2:3]
	v_mov_b64_e32 v[6:7], v[2:3]
	v_mov_b64_e32 v[8:9], v[2:3]
	v_mov_b64_e32 v[10:11], v[2:3]
	v_mov_b64_e32 v[12:13], v[2:3]
	v_mov_b64_e32 v[14:15], v[2:3]
	v_mov_b64_e32 v[16:17], v[2:3]
	v_mov_b64_e32 v[18:19], v[2:3]
	v_mov_b64_e32 v[20:21], v[2:3]
	v_mov_b64_e32 v[22:23], v[2:3]
	v_mov_b64_e32 v[24:25], v[2:3]
	v_mov_b64_e32 v[26:27], v[2:3]
	v_mov_b64_e32 v[28:29], v[2:3]
	v_mov_b64_e32 v[30:31], v[2:3]
	v_mov_b64_e32 v[32:33], v[2:3]
	v_mov_b64_e32 v[34:35], v[2:3]
	v_mov_b64_e32 v[36:37], v[2:3]
	v_mov_b64_e32 v[38:39], v[2:3]
	v_mov_b64_e32 v[40:41], v[2:3]
	v_mov_b64_e32 v[42:43], v[2:3]
	v_mov_b64_e32 v[44:45], v[2:3]
	v_mov_b64_e32 v[46:47], v[2:3]
	v_mov_b64_e32 v[48:49], v[2:3]
	v_mov_b64_e32 v[50:51], v[2:3]
	v_mov_b64_e32 v[52:53], v[2:3]
	v_mov_b64_e32 v[54:55], v[2:3]
	v_mov_b64_e32 v[56:57], v[2:3]
	v_mov_b64_e32 v[58:59], v[2:3]
	v_mov_b64_e32 v[60:61], v[2:3]
	v_mov_b64_e32 v[62:63], v[2:3]
	v_mov_b64_e32 v[64:65], v[2:3]
	v_mov_b64_e32 v[66:67], v[2:3]
	v_mov_b64_e32 v[68:69], v[2:3]
	v_mov_b64_e32 v[70:71], v[2:3]
	v_mov_b64_e32 v[72:73], v[2:3]
	v_mov_b64_e32 v[74:75], v[2:3]
	v_mov_b64_e32 v[76:77], v[2:3]
	v_mov_b64_e32 v[78:79], v[2:3]
	v_mov_b64_e32 v[80:81], v[2:3]
	v_mov_b64_e32 v[82:83], v[2:3]
	v_mov_b64_e32 v[84:85], v[2:3]
	v_mov_b64_e32 v[86:87], v[2:3]
	v_mov_b64_e32 v[88:89], v[2:3]
	v_mov_b64_e32 v[90:91], v[2:3]
	v_mov_b64_e32 v[92:93], v[2:3]
	v_mov_b64_e32 v[94:95], v[2:3]
	v_mov_b64_e32 v[96:97], v[2:3]
	v_mov_b64_e32 v[98:99], v[2:3]
	v_mov_b64_e32 v[100:101], v[2:3]
	v_mov_b64_e32 v[102:103], v[2:3]
	v_mov_b64_e32 v[104:105], v[2:3]
	v_mov_b64_e32 v[106:107], v[2:3]
	v_mov_b64_e32 v[108:109], v[2:3]
	v_mov_b64_e32 v[110:111], v[2:3]
	v_mov_b64_e32 v[112:113], v[2:3]
	v_mov_b64_e32 v[114:115], v[2:3]
	v_mov_b64_e32 v[116:117], v[2:3]
	v_mov_b64_e32 v[118:119], v[2:3]
	v_mov_b64_e32 v[120:121], v[2:3]
	v_mov_b64_e32 v[122:123], v[2:3]
	v_mov_b64_e32 v[124:125], v[2:3]
	v_mov_b64_e32 v[126:127], v[2:3]
	v_mov_b64_e32 v[128:129], v[2:3]

; #define PG8_STAGE(bufoff, gbase) do { _Pragma("unroll") for (int _i = 0; _i < 2; ++_i) \
;         __builtin_amdgcn_global_load_lds((const unsigned*)((const char*)(gbase) + voff[_i]), (LAS unsigned*)(lds + (bufoff) + ldsw + _i * 8192), 16, 0, 0); } while (0)
; #define PG8_WAIT_V(n) asm volatile("s_waitcnt vmcnt(" #n ")" ::: "memory")
; #define PG8_BAR __builtin_amdgcn_s_barrier()
;     __device__ bool next(int i, Unit& u) const {
;         const long L = (long)i * G + c; if (L >= nwg) return false;
;         int wgid = (int)L; { const int q = nwg / 8, r = nwg % 8, xcd = wgid % 8, off = wgid / 8; wgid = (xcd < r ? xcd * (q + 1) : r * (q + 1) + (xcd - r) * q) + off; }
;         const int nig = 8 * nN, gid = wgid / nig, fm = gid * 8, gsz = (nM - fm) < 8 ? (nM - fm) : 8;
;         u.pm = fm + ((wgid % nig) % gsz); u.pn = (wgid % nig) / gsz; return true;
;     }
;     ...
;     const char* cA = (const char*)gA + (size_t)cur.pm * tstep; const char* cB = (const char*)gBt + (size_t)cur.pn * tstep;
;     PG8_STAGE(PG8_SB(0, 0), cB); PG8_STAGE(PG8_SA(0, 0), cA); PG8_STAGE(PG8_SB(0, 1), cB + hstep); PG8_STAGE(PG8_SA(0, 1), cA + hstep);
;     if (wr == 1) PG8_BAR;
;     PG8_WAIT_V(4); PG8_BAR;
;     PG8_STAGE(PG8_SB(1, 0), cB + kstep); PG8_STAGE(PG8_SA(1, 0), cA + kstep); PG8_STAGE(PG8_SB(1, 1), cB + hstep + kstep);
;     PG8_WAIT_V(6); PG8_BAR;
;     for (;;) {
;         const bool has_next = S.next(ui + 1, nxt);
;         const char* nA = has_next ? (const char*)gA + (size_t)nxt.pm * tstep : cA; const char* nB = has_next ? (const char*)gBt + (size_t)nxt.pn * tstep : cB;
.LBB0_1559:
	v_bfe_u32 v18, v8, 4, 2
	v_and_b32_e32 v9, 15, v8
	v_lshlrev_b32_e32 v19, 4, v18
	v_lshlrev_b32_e32 v8, 2, v8
	v_lshl_or_b32 v1, s18, 6, v9
	v_lshl_or_b32 v9, v9, 6, v19
	s_lshl_b32 s0, s18, 13
	v_and_b32_e32 v8, 32, v8
	v_bitop3_b32 v19, v9, s0, v8 bitop3:0xde
	s_lshl_b32 s0, s7, 5
	v_mov_b32_e32 v133, v0
	s_and_b32 s7, s0, 0x60
	v_lshl_add_u64 v[10:11], s[14:15], 0, v[132:133]
	v_mov_b32_e32 v131, v0
	s_lshl_b32 s0, s7, 7
	v_lshl_add_u64 v[12:13], s[14:15], 0, v[130:131]
	v_bitop3_b32 v154, v9, s0, v8 bitop3:0xde
	s_add_i32 m0, s11, 0x18000
	v_lshl_add_u64 v[8:9], v[10:11], 0, s[88:89]
	v_lshl_add_u64 v[14:15], s[12:13], 0, v[132:133]
	s_waitcnt vmcnt(4)
	s_barrier
	global_load_lds_dwordx4 v[8:9], off
	v_lshl_add_u64 v[8:9], v[12:13], 0, s[88:89]
	s_add_i32 m0, s11, 0x1a000
	s_add_i32 s65, s11, 0x8000
	s_add_i32 s66, s11, 0xa000
	v_lshl_add_u64 v[16:17], s[12:13], 0, v[130:131]
	global_load_lds_dwordx4 v[8:9], off
	v_lshl_add_u64 v[8:9], v[14:15], 0, s[88:89]
	s_mov_b32 m0, s65
	s_add_u32 s0, s14, 0x40080
	global_load_lds_dwordx4 v[8:9], off
	v_lshl_add_u64 v[8:9], v[16:17], 0, s[88:89]
	s_mov_b32 m0, s66
	s_addc_u32 s1, s15, 0
	global_load_lds_dwordx4 v[8:9], off
	s_add_i32 m0, s11, 0x1c000
	v_lshl_add_u64 v[8:9], s[0:1], 0, v[132:133]
	global_load_lds_dwordx4 v[8:9], off
	v_lshl_add_u64 v[8:9], s[0:1], 0, v[130:131]
	s_add_i32 m0, s11, 0x1e000
	s_sext_i32_i16 s4, s40
	global_load_lds_dwordx4 v[8:9], off
	v_lshlrev_b32_e32 v8, 14, v5
	v_and_b32_e32 v8, 0xffff8000, v8
	v_lshl_add_u32 v6, v6, 11, v8
	v_and_b32_e32 v5, 1, v5
	v_lshl_or_b32 v5, v5, 6, v6
	v_lshl_add_u32 v150, v7, 1, v5
	v_lshlrev_b32_e32 v5, 14, v2
	v_and_b32_e32 v5, 0xffff8000, v5
	s_waitcnt vmcnt(6)
	v_lshl_add_u32 v3, v3, 11, v5
	v_and_b32_e32 v2, 1, v2
	v_lshl_or_b32 v2, v2, 6, v3
	v_lshl_or_b32 v155, v18, 2, s7
	v_mov_b32_e32 v151, v0
	v_lshl_add_u32 v152, v4, 1, v2
	v_mov_b32_e32 v153, v0
	s_mov_b32 s67, 0
	v_add_u32_e32 v156, 0, v19
	s_barrier
.LBB0_1560:
	s_add_i32 s67, s67, 1
	s_mul_i32 s0, s67, s3
	s_mul_hi_u32 s1, s67, s96
	s_add_i32 s1, s1, s0
	s_mul_i32 s0, s67, s96
	s_add_u32 s52, s0, s2
	s_addc_u32 s53, s1, s33
	v_mov_b64_e32 v[2:3], s[20:21]
	v_cmp_ge_i64_e64 s[44:45], s[52:53], v[2:3]
	s_and_b64 vcc, exec, s[44:45]
	s_cbranch_vccnz .LBB0_1562
	s_ashr_i32 s0, s52, 31
	s_lshr_b32 s0, s0, 29
	s_add_i32 s0, s52, s0
	s_ashr_i32 s1, s0, 3
	s_and_b32 s0, s0, -8
	s_sub_i32 s0, s52, s0
	s_cmp_lt_i32 s0, 0
	s_cselect_b32 s7, s61, s60
	s_mul_i32 s0, s7, s0
	s_add_i32 s0, s0, s1
	s_mul_hi_i32 s1, s0, 0x2e8ba2e9
	s_lshr_b32 s7, s1, 31
	s_ashr_i32 s1, s1, 5
	s_add_i32 s1, s1, s7
	s_lshl_b32 s7, s1, 3
	s_sub_i32 s18, s5, s7
	s_min_i32 s18, s18, 8
	s_abs_i32 s19, s18
	v_cvt_f32_u32_e32 v2, s19
	s_sub_i32 s23, 0, s19
	s_mulk_i32 s1, 0xb0
	s_sub_i32 s0, s0, s1
	v_rcp_iflag_f32_e32 v2, v2
	s_abs_i32 s1, s0
	s_xor_b32 s22, s0, s18
	s_ashr_i32 s22, s22, 31
	v_mul_f32_e32 v2, 0x4f7ffffe, v2
	v_cvt_u32_f32_e32 v2, v2
	s_nop 0
	v_readfirstlane_b32 s28, v2
	s_mul_i32 s23, s23, s28
	s_mul_hi_u32 s23, s28, s23
	s_add_i32 s28, s28, s23
	s_mul_hi_u32 s23, s1, s28
	s_mul_i32 s28, s23, s19
	s_sub_i32 s1, s1, s28
	s_add_i32 s29, s23, 1
	s_sub_i32 s28, s1, s19
	s_cmp_ge_u32 s1, s19
	s_cselect_b32 s23, s29, s23
	s_cselect_b32 s1, s28, s1
	s_add_i32 s28, s23, 1
	s_cmp_ge_u32 s1, s19
	s_cselect_b32 s1, s28, s23
	s_xor_b32 s1, s1, s22
	s_sub_i32 s40, s1, s22
	s_mul_i32 s1, s40, s18
	s_sub_i32 s0, s0, s1
	s_add_i32 s48, s0, s7
.LBB0_1562:
	s_ashr_i32 s49, s48, 31
	v_mov_b64_e32 v[2:3], s[20:21]
	s_lshl_b64 s[0:1], s[48:49], 19
	v_cmp_lt_i64_e32 vcc, s[52:53], v[2:3]
	s_add_u32 s52, s24, s0
	s_addc_u32 s53, s25, s1
	s_and_b64 s[0:1], vcc, exec
	s_cselect_b32 s7, s53, s13
	s_cselect_b32 s18, s52, s12
	s_ashr_i32 s41, s40, 31
	s_lshl_b64 s[0:1], s[40:41], 19
	s_add_u32 s56, s46, s0
	s_addc_u32 s57, s47, s1
	s_and_b64 s[0:1], vcc, exec
	s_cselect_b32 s19, s57, s15
	s_cselect_b32 s22, s56, s14
	s_add_u32 s12, s12, 0x40080
	s_addc_u32 s13, s13, 0
	s_add_u32 s23, s14, 0x100
	v_mov_b32_e32 v2, 0
	v_mov_b32_e32 v3, 0
	s_addc_u32 s28, s15, 0
	s_mov_b32 s29, -2
	v_mov_b64_e32 v[4:5], v[2:3]
	v_mov_b64_e32 v[6:7], v[2:3]
	v_mov_b64_e32 v[8:9], v[2:3]
	v_mov_b64_e32 v[10:11], v[2:3]
	v_mov_b64_e32 v[12:13], v[2:3]
	v_mov_b64_e32 v[14:15], v[2:3]
	v_mov_b64_e32 v[16:17], v[2:3]
	v_mov_b64_e32 v[18:19], v[2:3]
	v_mov_b64_e32 v[20:21], v[2:3]
	v_mov_b64_e32 v[22:23], v[2:3]
	v_mov_b64_e32 v[24:25], v[2:3]
	v_mov_b64_e32 v[26:27], v[2:3]
	v_mov_b64_e32 v[28:29], v[2:3]
	v_mov_b64_e32 v[30:31], v[2:3]
	v_mov_b64_e32 v[32:33], v[2:3]
	v_mov_b64_e32 v[34:35], v[2:3]
	v_mov_b64_e32 v[36:37], v[2:3]
	v_mov_b64_e32 v[38:39], v[2:3]
	v_mov_b64_e32 v[40:41], v[2:3]
	v_mov_b64_e32 v[42:43], v[2:3]
	v_mov_b64_e32 v[44:45], v[2:3]
	v_mov_b64_e32 v[46:47], v[2:3]
	v_mov_b64_e32 v[48:49], v[2:3]
	v_mov_b64_e32 v[50:51], v[2:3]
	v_mov_b64_e32 v[52:53], v[2:3]
	v_mov_b64_e32 v[54:55], v[2:3]
	v_mov_b64_e32 v[56:57], v[2:3]
	v_mov_b64_e32 v[58:59], v[2:3]
	v_mov_b64_e32 v[60:61], v[2:3]
	v_mov_b64_e32 v[62:63], v[2:3]
	v_mov_b64_e32 v[64:65], v[2:3]
	v_mov_b64_e32 v[66:67], v[2:3]
	v_mov_b64_e32 v[68:69], v[2:3]
	v_mov_b64_e32 v[70:71], v[2:3]
	v_mov_b64_e32 v[72:73], v[2:3]
	v_mov_b64_e32 v[74:75], v[2:3]
	v_mov_b64_e32 v[76:77], v[2:3]
	v_mov_b64_e32 v[78:79], v[2:3]
	v_mov_b64_e32 v[80:81], v[2:3]
	v_mov_b64_e32 v[82:83], v[2:3]
	v_mov_b64_e32 v[84:85], v[2:3]
	v_mov_b64_e32 v[86:87], v[2:3]
	v_mov_b64_e32 v[88:89], v[2:3]
	v_mov_b64_e32 v[90:91], v[2:3]
	v_mov_b64_e32 v[92:93], v[2:3]
	v_mov_b64_e32 v[94:95], v[2:3]
	v_mov_b64_e32 v[96:97], v[2:3]
	v_mov_b64_e32 v[98:99], v[2:3]
	v_mov_b64_e32 v[100:101], v[2:3]
	v_mov_b64_e32 v[102:103], v[2:3]
	v_mov_b64_e32 v[104:105], v[2:3]
	v_mov_b64_e32 v[106:107], v[2:3]
	v_mov_b64_e32 v[108:109], v[2:3]
	v_mov_b64_e32 v[110:111], v[2:3]
	v_mov_b64_e32 v[112:113], v[2:3]
	v_mov_b64_e32 v[114:115], v[2:3]
	v_mov_b64_e32 v[116:117], v[2:3]
	v_mov_b64_e32 v[118:119], v[2:3]
	v_mov_b64_e32 v[120:121], v[2:3]
	v_mov_b64_e32 v[122:123], v[2:3]
	v_mov_b64_e32 v[124:125], v[2:3]
	v_mov_b64_e32 v[126:127], v[2:3]
	v_mov_b64_e32 v[128:129], v[2:3]

;     ...
; #pragma unroll
;         for (int a = 0; a < 2; ++a)
; #pragma unroll
;             for (int b = 0; b < 2; ++b)
; #pragma unroll
;                 for (int m = 0; m < 4; ++m)
; #pragma unroll
;                     for (int n = 0; n < 2; ++n) acc[a][b][m][n] = (f32x4){0.f, 0.f, 0.f, 0.f};
;         cur = nxt; cA = nA; cB = nB; ++ui;
.LBB0_1648:
	s_add_u32 s22, s52, 0x100
	v_mov_b32_e32 v2, 0
	v_mov_b32_e32 v3, 0
	s_addc_u32 s23, s53, 0
	s_mov_b32 s28, -2
	v_mov_b64_e32 v[4:5], v[2:3]
	v_mov_b64_e32 v[6:7], v[2:3]
	v_mov_b64_e32 v[8:9], v[2:3]
	v_mov_b64_e32 v[10:11], v[2:3]
	v_mov_b64_e32 v[12:13], v[2:3]
	v_mov_b64_e32 v[14:15], v[2:3]
	v_mov_b64_e32 v[16:17], v[2:3]
	v_mov_b64_e32 v[18:19], v[2:3]
	v_mov_b64_e32 v[20:21], v[2:3]
	v_mov_b64_e32 v[22:23], v[2:3]
	v_mov_b64_e32 v[24:25], v[2:3]
	v_mov_b64_e32 v[26:27], v[2:3]
	v_mov_b64_e32 v[28:29], v[2:3]
	v_mov_b64_e32 v[30:31], v[2:3]
	v_mov_b64_e32 v[32:33], v[2:3]
	v_mov_b64_e32 v[34:35], v[2:3]
	v_mov_b64_e32 v[36:37], v[2:3]
	v_mov_b64_e32 v[38:39], v[2:3]
	v_mov_b64_e32 v[40:41], v[2:3]
	v_mov_b64_e32 v[42:43], v[2:3]
	v_mov_b64_e32 v[44:45], v[2:3]
	v_mov_b64_e32 v[46:47], v[2:3]
	v_mov_b64_e32 v[48:49], v[2:3]
	v_mov_b64_e32 v[50:51], v[2:3]
	v_mov_b64_e32 v[52:53], v[2:3]
	v_mov_b64_e32 v[54:55], v[2:3]
	v_mov_b64_e32 v[56:57], v[2:3]
	v_mov_b64_e32 v[58:59], v[2:3]
	v_mov_b64_e32 v[60:61], v[2:3]
	v_mov_b64_e32 v[62:63], v[2:3]
	v_mov_b64_e32 v[64:65], v[2:3]
	v_mov_b64_e32 v[66:67], v[2:3]
	v_mov_b64_e32 v[68:69], v[2:3]
	v_mov_b64_e32 v[70:71], v[2:3]
	v_mov_b64_e32 v[72:73], v[2:3]
	v_mov_b64_e32 v[74:75], v[2:3]
	v_mov_b64_e32 v[76:77], v[2:3]
	v_mov_b64_e32 v[78:79], v[2:3]
	v_mov_b64_e32 v[80:81], v[2:3]
	v_mov_b64_e32 v[82:83], v[2:3]
	v_mov_b64_e32 v[84:85], v[2:3]
	v_mov_b64_e32 v[86:87], v[2:3]
	v_mov_b64_e32 v[88:89], v[2:3]
	v_mov_b64_e32 v[90:91], v[2:3]
	v_mov_b64_e32 v[92:93], v[2:3]
	v_mov_b64_e32 v[94:95], v[2:3]
	v_mov_b64_e32 v[96:97], v[2:3]
	v_mov_b64_e32 v[98:99], v[2:3]
	v_mov_b64_e32 v[100:101], v[2:3]
	v_mov_b64_e32 v[102:103], v[2:3]
	v_mov_b64_e32 v[104:105], v[2:3]
	v_mov_b64_e32 v[106:107], v[2:3]
	v_mov_b64_e32 v[108:109], v[2:3]
	v_mov_b64_e32 v[110:111], v[2:3]
	v_mov_b64_e32 v[112:113], v[2:3]
	v_mov_b64_e32 v[114:115], v[2:3]
	v_mov_b64_e32 v[116:117], v[2:3]
	v_mov_b64_e32 v[118:119], v[2:3]
	v_mov_b64_e32 v[120:121], v[2:3]
	v_mov_b64_e32 v[122:123], v[2:3]
	v_mov_b64_e32 v[124:125], v[2:3]
	v_mov_b64_e32 v[126:127], v[2:3]
	v_mov_b64_e32 v[128:129], v[2:3]

; #define PG8_STAGE(bufoff, gbase) do { _Pragma("unroll") for (int _i = 0; _i < 2; ++_i) \
;         __builtin_amdgcn_global_load_lds((const unsigned*)((const char*)(gbase) + voff[_i]), (LAS unsigned*)(lds + (bufoff) + ldsw + _i * 8192), 16, 0, 0); } while (0)
; #define PG8_WAIT_V(n) asm volatile("s_waitcnt vmcnt(" #n ")" ::: "memory")
; #define PG8_BAR __builtin_amdgcn_s_barrier()
;     ...
;     for (int i = 0; i < 2; ++i) { int R, C; stage_rc(tid * 16 + i * 8192, R, C); voff[i] = (unsigned)(R * K + C) * 2u; }
;     const size_t kstep = (size_t)(GBK * 2);
;     const size_t hstep = (size_t)GHALF * K * 2;
;     const size_t tstep = 2 * hstep;
;     const unsigned ldsw = (unsigned)wid * 1024u;
;     const int aoff = lds_byte(wr * 64 + fr, fq * 8), boff = lds_byte(wc * 32 + fr, fq * 8);
;     ...
;     Unit cur, nxt; int ui = 0;
;     if (!S.next(0, cur)) return;
;     f32x4 acc[2][2][4][2];
; #pragma unroll
;     for (int a = 0; a < 2; ++a)
; #pragma unroll
;         for (int b = 0; b < 2; ++b)
; #pragma unroll
;             for (int m = 0; m < 4; ++m)
; #pragma unroll
;                 for (int n = 0; n < 2; ++n) acc[a][b][m][n] = (f32x4){0.f, 0.f, 0.f, 0.f};
;     bf16x8 At[4][2], B0[2][2], B1[2][2];
;     const char* cA = (const char*)gA + (size_t)cur.pm * tstep; const char* cB = (const char*)gBt + (size_t)cur.pn * tstep;
;     PG8_STAGE(PG8_SB(0, 0), cB); PG8_STAGE(PG8_SA(0, 0), cA); PG8_STAGE(PG8_SB(0, 1), cB + hstep); PG8_STAGE(PG8_SA(0, 1), cA + hstep);
;     if (wr == 1) PG8_BAR;
;     PG8_WAIT_V(4); PG8_BAR;
;     PG8_STAGE(PG8_SB(1, 0), cB + kstep); PG8_STAGE(PG8_SA(1, 0), cA + kstep); PG8_STAGE(PG8_SB(1, 1), cB + hstep + kstep);
;     PG8_WAIT_V(6); PG8_BAR;
.LBB0_1831:
	v_bfe_u32 v154, v14, 4, 2
	v_and_b32_e32 v15, 15, v14
	v_lshlrev_b32_e32 v20, 4, v154
	v_lshlrev_b32_e32 v14, 2, v14
	v_lshl_or_b32 v1, s13, 6, v15
	v_lshl_or_b32 v15, v15, 6, v20
	s_lshl_b32 s0, s13, 13
	v_and_b32_e32 v14, 32, v14
	v_bitop3_b32 v20, v15, s0, v14 bitop3:0xde
	s_lshl_b32 s0, s12, 5
	s_and_b32 s20, s0, 0x60
	s_add_i32 m0, s7, 0x18000
	v_lshl_add_u64 v[2:3], v[2:3], 0, s[88:89]
	v_lshl_add_u64 v[16:17], s[44:45], 0, v[130:131]
	s_lshl_b32 s0, s20, 7
	s_waitcnt vmcnt(4)
	s_barrier
	global_load_lds_dwordx4 v[2:3], off
	v_lshl_add_u64 v[2:3], v[4:5], 0, s[88:89]
	s_add_i32 m0, s7, 0x1a000
	s_add_i32 s22, s7, 0x8000
	s_add_i32 s23, s7, 0xa000
	v_lshl_add_u64 v[18:19], s[44:45], 0, v[132:133]
	v_bitop3_b32 v155, v15, s0, v14 bitop3:0xde
	global_load_lds_dwordx4 v[2:3], off
	v_lshl_add_u64 v[2:3], v[16:17], 0, s[88:89]
	s_mov_b32 m0, s22
	s_add_u32 s0, s10, 0xb0080
	global_load_lds_dwordx4 v[2:3], off
	v_lshl_add_u64 v[2:3], v[18:19], 0, s[88:89]
	s_mov_b32 m0, s23
	s_addc_u32 s1, s11, 0
	global_load_lds_dwordx4 v[2:3], off
	s_add_i32 m0, s7, 0x1c000
	v_lshl_add_u64 v[2:3], s[0:1], 0, v[130:131]
	global_load_lds_dwordx4 v[2:3], off
	v_lshl_add_u64 v[2:3], s[0:1], 0, v[132:133]
	s_add_i32 m0, s7, 0x1e000
	s_movk_i32 s14, 0xb00
	global_load_lds_dwordx4 v[2:3], off
	v_lshrrev_b32_e32 v3, 1, v6
	v_mul_lo_u32 v2, v8, s14
	s_mov_b32 s15, 0xb000
	v_mad_u64_u32 v[2:3], s[0:1], v3, s15, v[2:3]
	v_or_b32_e32 v2, v2, v7
	v_readlane_b32 s12, v254, 28
	v_add_lshl_u32 v2, v2, v9, 1
	v_mov_b32_e32 v3, v0
	v_readlane_b32 s13, v254, 29
	s_waitcnt vmcnt(6)
	s_mov_b32 s28, -2
	v_add_u32_e32 v156, 0, v20
	v_lshl_add_u64 v[150:151], s[12:13], 0, v[2:3]
	v_lshrrev_b32_e32 v3, 1, v10
	v_mul_lo_u32 v2, v12, s14
	v_mad_u64_u32 v[2:3], s[0:1], v3, s15, v[2:3]
	v_or_b32_e32 v2, v2, v11
	v_add_lshl_u32 v2, v2, v13, 1
	v_mov_b32_e32 v3, v0
	v_lshl_add_u64 v[152:153], s[12:13], 0, v[2:3]
	v_mov_b32_e32 v2, 0
	v_mov_b32_e32 v3, 0
	s_mov_b64 s[12:13], 0xb0b0080
	v_mov_b64_e32 v[4:5], v[2:3]
	v_mov_b64_e32 v[6:7], v[2:3]
	v_mov_b64_e32 v[8:9], v[2:3]
	v_mov_b64_e32 v[10:11], v[2:3]
	v_mov_b64_e32 v[12:13], v[2:3]
	v_mov_b64_e32 v[14:15], v[2:3]
	v_mov_b64_e32 v[16:17], v[2:3]
	v_mov_b64_e32 v[18:19], v[2:3]
	v_mov_b64_e32 v[20:21], v[2:3]
	v_mov_b64_e32 v[22:23], v[2:3]
	v_mov_b64_e32 v[24:25], v[2:3]
	v_mov_b64_e32 v[26:27], v[2:3]
	v_mov_b64_e32 v[28:29], v[2:3]
	v_mov_b64_e32 v[30:31], v[2:3]
	v_mov_b64_e32 v[32:33], v[2:3]
	v_mov_b64_e32 v[34:35], v[2:3]
	v_mov_b64_e32 v[36:37], v[2:3]
	v_mov_b64_e32 v[38:39], v[2:3]
	v_mov_b64_e32 v[40:41], v[2:3]
	v_mov_b64_e32 v[42:43], v[2:3]
	v_mov_b64_e32 v[44:45], v[2:3]
	v_mov_b64_e32 v[46:47], v[2:3]
	v_mov_b64_e32 v[48:49], v[2:3]
	v_mov_b64_e32 v[50:51], v[2:3]
	v_mov_b64_e32 v[52:53], v[2:3]
	v_mov_b64_e32 v[54:55], v[2:3]
	v_mov_b64_e32 v[56:57], v[2:3]
	v_mov_b64_e32 v[58:59], v[2:3]
	v_mov_b64_e32 v[60:61], v[2:3]
	v_mov_b64_e32 v[62:63], v[2:3]
	v_mov_b64_e32 v[64:65], v[2:3]
	v_mov_b64_e32 v[66:67], v[2:3]
	v_mov_b64_e32 v[68:69], v[2:3]
	v_mov_b64_e32 v[70:71], v[2:3]
	v_mov_b64_e32 v[72:73], v[2:3]
	v_mov_b64_e32 v[74:75], v[2:3]
	v_mov_b64_e32 v[76:77], v[2:3]
	v_mov_b64_e32 v[78:79], v[2:3]
	v_mov_b64_e32 v[80:81], v[2:3]
	v_mov_b64_e32 v[82:83], v[2:3]
	v_mov_b64_e32 v[84:85], v[2:3]
	v_mov_b64_e32 v[86:87], v[2:3]
	v_mov_b64_e32 v[88:89], v[2:3]
	v_mov_b64_e32 v[90:91], v[2:3]
	v_mov_b64_e32 v[92:93], v[2:3]
	v_mov_b64_e32 v[94:95], v[2:3]
	v_mov_b64_e32 v[96:97], v[2:3]
	v_mov_b64_e32 v[98:99], v[2:3]
	v_mov_b64_e32 v[100:101], v[2:3]
	v_mov_b64_e32 v[102:103], v[2:3]
	v_mov_b64_e32 v[104:105], v[2:3]
	v_mov_b64_e32 v[106:107], v[2:3]
	v_mov_b64_e32 v[108:109], v[2:3]
	v_mov_b64_e32 v[110:111], v[2:3]
	v_mov_b64_e32 v[112:113], v[2:3]
	v_mov_b64_e32 v[114:115], v[2:3]
	v_mov_b64_e32 v[116:117], v[2:3]
	v_mov_b64_e32 v[118:119], v[2:3]
	v_mov_b64_e32 v[120:121], v[2:3]
	v_mov_b64_e32 v[122:123], v[2:3]
	v_mov_b64_e32 v[124:125], v[2:3]
	v_mov_b64_e32 v[126:127], v[2:3]
	v_mov_b64_e32 v[128:129], v[2:3]
	s_barrier
